# pipelined w_in convert loop (old dead path removed) + scalarised packed-f32 VALU in diff and stick-breaking attention loops
# speedup vs baseline: 1.0075x; 1.0075x over previous
.Lcv_done:
	s_waitcnt vmcnt(0) lgkmcnt(0)
	s_lshl_b32 s0, s2, 3
	s_add_i32 s84, s79, s0
	s_lshl_b32 s86, s80, 3
	v_writelane_b32 v254, s0, 0
	s_mov_b64 s[4:5], s[88:89]
	s_cmp_gt_i32 s84, 0xe0ff
	v_mbcnt_lo_u32_b32 v98, -1, 0
	v_mbcnt_hi_u32_b32 v98, -1, v98
	s_cbranch_scc1 .LBB0_75
	s_lshl_b32 s0, s79, 14
	v_ashrrev_i32_e32 v14, 5, v98
	v_and_b32_e32 v2, 31, v98
	s_movk_i32 s1, 0x84
	s_add_i32 s0, s0, 0
	v_lshlrev_b32_e32 v4, 2, v2
	v_mul_lo_u32 v5, v14, s1
	v_add3_u32 v15, s0, v4, v5
	v_lshlrev_b32_e32 v5, 3, v98
	v_ashrrev_i32_e32 v4, 3, v98
	v_and_b32_e32 v12, 56, v5
	v_mul_u32_u24_e32 v5, 0x84, v12
	v_lshlrev_b32_e32 v6, 2, v4
	v_add3_u32 v16, s0, v5, v6
	s_load_dwordx2 s[0:1], s[4:5], 0x98
	v_add_u32_e32 v6, 8, v4
	v_add_u32_e32 v8, 16, v4
	v_add_u32_e32 v10, 24, v4
	s_mov_b32 s7, 0
	s_waitcnt lgkmcnt(0)
	s_add_u32 s3, s0, 0x200000
	v_mov_b32_e32 v3, 0
	v_ashrrev_i32_e32 v5, 31, v4
	v_ashrrev_i32_e32 v7, 31, v6
	v_ashrrev_i32_e32 v9, 31, v8
	v_ashrrev_i32_e32 v11, 31, v10
	s_addc_u32 s25, s1, 0
	s_lshl_b32 s26, s84, 5
	s_lshl_b32 s27, s80, 8
	s_lshl_b32 s28, s84, 3
	s_lshl_b32 s29, s80, 6
	s_movk_i32 s30, 0x1000
	s_movk_i32 s31, 0x2000
	s_movk_i32 s33, 0x3000
	s_movk_i32 s34, 0x4000
	s_movk_i32 s35, 0x5000
	s_movk_i32 s36, 0x6000
	s_movk_i32 s37, 0x7000
	s_mov_b32 s38, 0x8000
	s_mov_b32 s39, 0x9000
	s_mov_b32 s40, 0xa000
	s_mov_b32 s41, 0xb000
	s_mov_b32 s42, 0xc000
	s_mov_b32 s43, 0xd000
	s_mov_b32 s44, 0xe000
	s_mov_b32 s45, 0xf000
	s_mov_b64 s[10:11], 0x7000000
	s_mov_b32 s46, 0x10000
	s_mov_b32 s47, 0x14000
	s_mov_b32 s48, 0x18000
	s_mov_b32 s49, 0x1c000
	s_mov_b32 s50, 0x20000
	s_mov_b32 s51, 0x24000
	s_mov_b32 s52, 0x28000
	s_mov_b32 s53, 0x2c000
	s_mov_b32 s54, 0x30000
	s_mov_b32 s55, 0x34000
	s_mov_b32 s56, 0x38000
	s_mov_b32 s57, 0x3c000
	s_mov_b32 s58, 0x40000
	s_mov_b32 s59, 0x44000
	s_mov_b32 s60, 0x48000
	s_mov_b32 s61, 0x4c000
	s_mov_b32 s62, 0x50000
	s_mov_b32 s63, 0x54000
	s_mov_b32 s64, 0x58000
	s_mov_b32 s65, 0x5c000
	s_mov_b32 s66, 0x60000
	s_mov_b32 s67, 0x64000
	s_mov_b32 s68, 0x68000
	s_mov_b32 s69, 0x6c000
	s_mov_b32 s70, 0x70000
	s_mov_b32 s71, 0x74000
	s_mov_b32 s72, 0x78000
	s_mov_b32 s73, 0x7c000
	s_mov_b64 s[12:13], 0x6800000
	s_mov_b64 s[14:15], 0x5800000
	s_movk_i32 s74, 0x4800
	s_movk_i32 s75, 0x2400
	v_lshlrev_b32_e32 v2, 2, v2
	v_add_u32_e32 v17, 0x400, v15
	v_add_u32_e32 v18, 0x800, v15
	v_add_u32_e32 v19, 0xc00, v15
	v_add_u32_e32 v20, 0x1000, v15
	v_add_u32_e32 v21, 0x1400, v15
	v_add_u32_e32 v22, 0x1800, v15
	v_add_u32_e32 v23, 0x1c00, v15
	v_lshlrev_b32_e32 v12, 1, v12
	s_mov_b32 s76, s84
	s_branch .LBB0_22
.LBB0_21:
	s_add_i32 s76, s76, s86
	s_add_i32 s26, s26, s27
	s_add_i32 s28, s28, s29
	s_cmp_lt_i32 s76, 0xe100
	s_cbranch_scc0 .LBB0_75

.LBB0_35:
	s_mov_b64 s[0:1], 0
.LBB0_36:
	s_branch .LBB0_21
.LBB0_75:
	s_mov_b64 s[12:13], s[88:89]
	s_mov_b64 s[0:1], s[88:89]
	s_load_dwordx2 s[10:11], s[12:13], 0x98
	s_load_dwordx2 s[16:17], s[0:1], 0x0
	s_mov_b64 s[4:5], 0xe400000
	v_ashrrev_i32_e32 v99, 31, v98
	v_lshlrev_b32_e32 v120, 2, v98
	s_waitcnt lgkmcnt(0)
	s_add_u32 s14, s10, 0xe400000
	s_addc_u32 s15, s11, 0
	s_add_i32 s28, s84, s86
	s_cmpk_lt_i32 s28, 0x4000
	s_cselect_b64 s[0:1], -1, 0
	v_writelane_b32 v254, s0, 1
	s_cmpk_gt_i32 s28, 0x3fff
	s_nop 0
	v_writelane_b32 v254, s1, 2
	s_mov_b32 s0, s84
	s_cbranch_scc0 .LBB0_78
	s_cmpk_gt_i32 s0, 0x3fff
	s_cbranch_scc0 .LBB0_81

.LBB0_411:
	s_and_b32 s79, s10, 1
	s_add_i32 s10, s78, 0x80
	v_cmp_le_i32_e32 vcc, s10, v210
	s_xor_b64 s[10:11], s[0:1], -1
	s_and_b64 s[10:11], vcc, s[10:11]
	s_and_saveexec_b64 s[96:97], s[10:11]
	s_cbranch_execz .LBB0_413
	s_mul_i32 s10, s79, 0x8c00
	s_add_i32 s10, s10, 0
	v_add_u32_e32 v216, s10, v211
	v_add_u32_e32 v172, v216, v214
	ds_read_b128 v[66:69], v172
	ds_read_b128 v[146:149], v172 offset:32
	ds_read_b128 v[82:85], v172 offset:8704
	ds_read_b128 v[150:153], v172 offset:8736
	s_add_i32 s11, s78, 0xbf
	v_cmp_lt_i32_e64 s[12:13], s11, v190
	s_waitcnt lgkmcnt(3)
	v_mfma_f32_32x32x16_bf16 v[66:81], v[66:69], v[122:125], 0
	s_waitcnt lgkmcnt(1)
	v_mfma_f32_32x32x16_bf16 v[82:97], v[82:85], v[122:125], 0
	v_mfma_f32_32x32x16_bf16 v[66:81], v[146:149], v[98:101], v[66:81]
	ds_read_b128 v[146:149], v172 offset:64
	ds_read_b128 v[154:157], v172 offset:96
	ds_read_b128 v[158:161], v172 offset:8768
	ds_read_b128 v[174:177], v172 offset:8800
	s_waitcnt lgkmcnt(4)
	v_mfma_f32_32x32x16_bf16 v[82:97], v[150:153], v[98:101], v[82:97]
	s_waitcnt lgkmcnt(3)
	v_mfma_f32_32x32x16_bf16 v[66:81], v[146:149], v[102:105], v[66:81]
	s_waitcnt lgkmcnt(1)
	v_mfma_f32_32x32x16_bf16 v[82:97], v[158:161], v[102:105], v[82:97]
	v_mfma_f32_32x32x16_bf16 v[66:81], v[154:157], v[106:109], v[66:81]
	ds_read_b128 v[146:149], v172 offset:128
	ds_read_b128 v[150:153], v172 offset:160
	ds_read_b128 v[154:157], v172 offset:8832
	ds_read_b128 v[158:161], v172 offset:8864
	s_waitcnt lgkmcnt(4)
	v_mfma_f32_32x32x16_bf16 v[82:97], v[174:177], v[106:109], v[82:97]
	s_waitcnt lgkmcnt(3)
	v_mfma_f32_32x32x16_bf16 v[66:81], v[146:149], v[110:113], v[66:81]
	s_waitcnt lgkmcnt(1)
	v_mfma_f32_32x32x16_bf16 v[82:97], v[154:157], v[110:113], v[82:97]
	v_mfma_f32_32x32x16_bf16 v[66:81], v[150:153], v[114:117], v[66:81]
	ds_read_b128 v[146:149], v172 offset:192
	ds_read_b128 v[150:153], v172 offset:224
	ds_read_b128 v[154:157], v172 offset:8896
	ds_read_b128 v[174:177], v172 offset:8928
	s_waitcnt lgkmcnt(4)
	v_mfma_f32_32x32x16_bf16 v[82:97], v[158:161], v[114:117], v[82:97]
	s_waitcnt lgkmcnt(3)
	v_mfma_f32_32x32x16_bf16 v[66:81], v[146:149], v[118:121], v[66:81]
	v_add3_u32 v146, s10, v212, v211
	s_waitcnt lgkmcnt(1)
	v_mfma_f32_32x32x16_bf16 v[82:97], v[154:157], v[118:121], v[82:97]
	v_mfma_f32_32x32x16_bf16 v[66:81], v[150:153], v[126:129], v[66:81]
	ds_read_b128 v[158:161], v146 offset:17408
	ds_read_b128 v[154:157], v146 offset:17440
	ds_read_b128 v[150:153], v146 offset:17472
	ds_read_b128 v[146:149], v146 offset:17504
	s_waitcnt lgkmcnt(4)
	v_mfma_f32_32x32x16_bf16 v[82:97], v[174:177], v[126:129], v[82:97]
	s_nop 11
	v_mul_f32_e32 v172, 0x3e0293ee, v82
	v_exp_f32_e64 v174, -|v172|
	v_mul_f32_e32 v175, 0x3e0293ee, v83
	v_exp_f32_e64 v176, -|v175|
	v_max_f32_e32 v172, 0, v172
	v_add_f32_e32 v174, 1.0, v174
	v_log_f32_e32 v174, v174
	v_max_f32_e32 v175, 0, v175
	v_mov_b32_e32 v194, v215
	v_add_f32_e32 v172, v172, v174
	v_add_f32_e32 v174, 1.0, v176
	v_log_f32_e32 v174, v174
	v_cmp_lt_i32_e64 s[10:11], 33, v194
	s_or_b64 s[10:11], s[12:13], s[10:11]
	v_cmp_lt_i32_e64 s[14:15], 34, v194
	v_add_f32_e32 v174, v175, v174
	v_mul_f32_e32 v175, 0x3e0293ee, v84
	v_exp_f32_e64 v176, -|v175|
	v_cndmask_b32_e64 v217, 0, v174, s[10:11]
	v_max_f32_e32 v175, 0, v175
	s_or_b64 s[14:15], s[12:13], s[14:15]
	v_add_f32_e32 v174, 1.0, v176
	v_mul_f32_e32 v176, 0x3e0293ee, v85
	v_log_f32_e32 v174, v174
	v_exp_f32_e64 v177, -|v176|
	v_cmp_lt_i32_e64 s[16:17], 35, v194
	s_or_b64 s[16:17], s[12:13], s[16:17]
	v_add_f32_e32 v174, v175, v174
	v_add_f32_e32 v175, 1.0, v177
	v_log_f32_e32 v175, v175
	v_cndmask_b32_e64 v222, 0, v174, s[14:15]
	v_max_f32_e32 v174, 0, v176
	v_cmp_lt_i32_e64 s[18:19], 36, v194
	v_add_f32_e32 v174, v174, v175
	v_mul_f32_e32 v175, 0x3e0293ee, v86
	v_exp_f32_e64 v176, -|v175|
	v_cndmask_b32_e64 v223, 0, v174, s[16:17]
	v_max_f32_e32 v175, 0, v175
	s_or_b64 s[18:19], s[12:13], s[18:19]
	v_add_f32_e32 v174, 1.0, v176
	v_mul_f32_e32 v176, 0x3e0293ee, v87
	v_log_f32_e32 v174, v174
	v_exp_f32_e64 v177, -|v176|
	v_cmp_lt_i32_e64 s[20:21], 37, v194
	s_or_b64 s[20:21], s[12:13], s[20:21]
	v_add_f32_e32 v174, v175, v174
	v_add_f32_e32 v175, 1.0, v177
	v_log_f32_e32 v175, v175
	v_cndmask_b32_e64 v224, 0, v174, s[18:19]
	v_max_f32_e32 v174, 0, v176
	v_cmp_lt_i32_e64 s[22:23], 38, v194
	v_add_f32_e32 v174, v174, v175
	v_mul_f32_e32 v175, 0x3e0293ee, v88
	v_exp_f32_e64 v176, -|v175|
	v_cndmask_b32_e64 v225, 0, v174, s[20:21]
	v_max_f32_e32 v175, 0, v175
	s_or_b64 s[22:23], s[12:13], s[22:23]
	v_add_f32_e32 v174, 1.0, v176
	v_mul_f32_e32 v176, 0x3e0293ee, v89
	v_log_f32_e32 v174, v174
	v_exp_f32_e64 v177, -|v176|
	v_cmp_lt_i32_e64 s[24:25], 39, v194
	s_or_b64 s[24:25], s[12:13], s[24:25]
	v_add_f32_e32 v174, v175, v174
	v_add_f32_e32 v175, 1.0, v177
	v_log_f32_e32 v175, v175
	v_cndmask_b32_e64 v226, 0, v174, s[22:23]
	v_max_f32_e32 v174, 0, v176
	v_cmp_lt_i32_e64 s[26:27], 48, v194
	v_add_f32_e32 v174, v174, v175
	v_mul_f32_e32 v175, 0x3e0293ee, v90
	v_exp_f32_e64 v176, -|v175|
	v_cndmask_b32_e64 v227, 0, v174, s[24:25]
	v_max_f32_e32 v175, 0, v175
	s_or_b64 s[30:31], s[12:13], s[26:27]
	v_add_f32_e32 v174, 1.0, v176
	v_mul_f32_e32 v176, 0x3e0293ee, v91
	v_log_f32_e32 v174, v174
	v_exp_f32_e64 v177, -|v176|
	v_cmp_lt_i32_e64 s[26:27], 49, v194
	s_or_b64 s[36:37], s[12:13], s[26:27]
	v_add_f32_e32 v174, v175, v174
	v_add_f32_e32 v175, 1.0, v177
	v_log_f32_e32 v175, v175
	v_cndmask_b32_e64 v228, 0, v174, s[30:31]
	v_max_f32_e32 v174, 0, v176
	v_cmp_lt_i32_e64 s[26:27], 50, v194
	v_add_f32_e32 v174, v174, v175
	v_mul_f32_e32 v175, 0x3e0293ee, v92
	v_exp_f32_e64 v176, -|v175|
	v_cndmask_b32_e64 v229, 0, v174, s[36:37]
	v_max_f32_e32 v175, 0, v175
	s_or_b64 s[40:41], s[12:13], s[26:27]
	v_add_f32_e32 v174, 1.0, v176
	v_mul_f32_e32 v176, 0x3e0293ee, v93
	v_log_f32_e32 v174, v174
	v_exp_f32_e64 v177, -|v176|
	v_cmp_lt_i32_e64 s[26:27], 51, v194
	s_or_b64 s[42:43], s[12:13], s[26:27]
	v_add_f32_e32 v174, v175, v174
	v_add_f32_e32 v175, 1.0, v177
	v_log_f32_e32 v175, v175
	v_cndmask_b32_e64 v230, 0, v174, s[40:41]
	v_max_f32_e32 v174, 0, v176
	v_cmp_lt_i32_e64 s[26:27], 52, v194
	v_add_f32_e32 v174, v174, v175
	v_mul_f32_e32 v175, 0x3e0293ee, v94
	v_exp_f32_e64 v176, -|v175|
	v_cndmask_b32_e64 v231, 0, v174, s[42:43]
	v_max_f32_e32 v175, 0, v175
	s_or_b64 s[48:49], s[12:13], s[26:27]
	v_add_f32_e32 v174, 1.0, v176
	v_mul_f32_e32 v176, 0x3e0293ee, v95
	v_log_f32_e32 v174, v174
	v_exp_f32_e64 v177, -|v176|
	v_cmp_lt_i32_e64 s[26:27], 53, v194
	s_or_b64 s[52:53], s[12:13], s[26:27]
	v_add_f32_e32 v174, v175, v174
	v_add_f32_e32 v175, 1.0, v177
	v_log_f32_e32 v175, v175
	v_cndmask_b32_e64 v232, 0, v174, s[48:49]
	v_max_f32_e32 v174, 0, v176
	v_cmp_lt_i32_e64 s[26:27], 54, v194
	v_add_f32_e32 v174, v174, v175
	v_mul_f32_e32 v175, 0x3e0293ee, v96
	v_exp_f32_e64 v176, -|v175|
	v_cndmask_b32_e64 v233, 0, v174, s[52:53]
	v_max_f32_e32 v175, 0, v175
	s_or_b64 s[56:57], s[12:13], s[26:27]
	v_add_f32_e32 v174, 1.0, v176
	v_mul_f32_e32 v176, 0x3e0293ee, v97
	v_log_f32_e32 v174, v174
	v_exp_f32_e64 v177, -|v176|
	v_cmp_lt_i32_e64 s[26:27], 55, v194
	s_or_b64 s[58:59], s[12:13], s[26:27]
	v_add_f32_e32 v174, v175, v174
	v_add_f32_e32 v175, 1.0, v177
	v_log_f32_e32 v175, v175
	v_cndmask_b32_e64 v234, 0, v174, s[56:57]
	v_max_f32_e32 v174, 0, v176
	v_mul_f32_e32 v178, 0x3e0293ee, v67
	v_add_f32_e32 v174, v174, v175
	v_cndmask_b32_e64 v235, 0, v174, s[58:59]
	v_mul_f32_e32 v174, 0x3e0293ee, v66
	v_exp_f32_e64 v176, -|v174|
	v_exp_f32_e64 v180, -|v178|
	v_max_f32_e32 v174, 0, v174
	v_max_f32_e32 v178, 0, v178
	v_add_f32_e32 v176, 1.0, v176
	v_log_f32_e32 v176, v176
	v_mul_f32_e32 v182, 0x3e0293ee, v69
	v_exp_f32_e64 v184, -|v182|
	v_max_f32_e32 v182, 0, v182
	v_add_f32_e32 v174, v174, v176
	v_add_f32_e32 v176, 1.0, v180
	v_log_f32_e32 v176, v176
	v_mul_f32_e32 v186, 0x3e0293ee, v71
	v_exp_f32_e64 v188, -|v186|
	v_max_f32_e32 v186, 0, v186
	v_add_f32_e32 v176, v178, v176
	v_mul_f32_e32 v178, 0x3e0293ee, v68
	v_exp_f32_e64 v180, -|v178|
	v_max_f32_e32 v178, 0, v178
	v_mul_f32_e32 v195, 0x3e0293ee, v73
	v_exp_f32_e64 v196, -|v195|
	v_add_f32_e32 v180, 1.0, v180
	v_log_f32_e32 v180, v180
	v_max_f32_e32 v195, 0, v195
	v_mul_f32_e32 v197, 0x3e0293ee, v75
	v_exp_f32_e64 v198, -|v197|
	v_add_f32_e32 v178, v178, v180
	v_add_f32_e32 v180, 1.0, v184
	v_log_f32_e32 v180, v180
	v_cmp_lt_i32_e64 s[60:61], 16, v194
	s_or_b64 s[60:61], s[12:13], s[60:61]
	v_cmp_lt_i32_e64 s[62:63], 17, v194
	v_add_f32_e32 v180, v182, v180
	v_mul_f32_e32 v182, 0x3e0293ee, v70
	v_exp_f32_e64 v184, -|v182|
	v_max_f32_e32 v182, 0, v182
	s_or_b64 s[62:63], s[12:13], s[62:63]
	v_cmp_lt_i32_e64 s[64:65], 18, v194
	v_add_f32_e32 v184, 1.0, v184
	v_log_f32_e32 v184, v184
	s_or_b64 s[64:65], s[12:13], s[64:65]
	v_cmp_lt_i32_e64 s[66:67], 19, v194
	s_or_b64 s[66:67], s[12:13], s[66:67]
	v_add_f32_e32 v182, v182, v184
	v_add_f32_e32 v184, 1.0, v188
	v_log_f32_e32 v184, v184
	v_cmp_lt_i32_e64 s[68:69], 20, v194
	s_or_b64 s[68:69], s[12:13], s[68:69]
	v_cmp_lt_i32_e64 s[70:71], 21, v194
	v_add_f32_e32 v184, v186, v184
	v_mul_f32_e32 v186, 0x3e0293ee, v72
	v_exp_f32_e64 v188, -|v186|
	v_max_f32_e32 v186, 0, v186
	s_or_b64 s[70:71], s[12:13], s[70:71]
	v_cmp_lt_i32_e32 vcc, 32, v194
	v_add_f32_e32 v188, 1.0, v188
	v_log_f32_e32 v188, v188
	s_or_b64 vcc, s[12:13], vcc
	v_cmp_lt_i32_e64 s[26:27], 0, v194
	v_cmp_lt_i32_e64 s[28:29], 1, v194
	v_add_f32_e32 v186, v186, v188
	v_add_f32_e32 v188, 1.0, v196
	v_log_f32_e32 v188, v188
	v_cmp_lt_i32_e64 s[34:35], 2, v194
	v_cmp_lt_i32_e64 s[38:39], 3, v194
	v_cndmask_b32_e32 v172, 0, v172, vcc
	v_add_f32_e32 v188, v195, v188
	v_mul_f32_e32 v195, 0x3e0293ee, v74
	v_exp_f32_e64 v196, -|v195|
	v_max_f32_e32 v195, 0, v195
	s_or_b64 s[26:27], s[12:13], s[26:27]
	s_or_b64 s[28:29], s[12:13], s[28:29]
	v_add_f32_e32 v196, 1.0, v196
	v_log_f32_e32 v196, v196
	s_or_b64 s[34:35], s[12:13], s[34:35]
	s_or_b64 s[38:39], s[12:13], s[38:39]
	v_add_f32_e32 v175, v172, v217
	v_add_f32_e32 v195, v195, v196
	v_add_f32_e32 v196, 1.0, v198
	v_log_f32_e32 v196, v196
	v_cndmask_b32_e64 v236, 0, v195, s[60:61]
	v_max_f32_e32 v195, 0, v197
	v_add_f32_e32 v177, v222, v223
	v_add_f32_e32 v195, v195, v196
	v_mul_f32_e32 v196, 0x3e0293ee, v76
	v_exp_f32_e64 v197, -|v196|
	v_cndmask_b32_e64 v237, 0, v195, s[62:63]
	v_max_f32_e32 v196, 0, v196
	v_add_f32_e32 v179, v224, v225
	v_add_f32_e32 v195, 1.0, v197
	v_mul_f32_e32 v197, 0x3e0293ee, v77
	v_log_f32_e32 v195, v195
	v_exp_f32_e64 v198, -|v197|
	v_add_f32_e32 v181, v226, v227
	v_cndmask_b32_e64 v174, 0, v174, s[26:27]
	v_add_f32_e32 v195, v196, v195
	v_add_f32_e32 v196, 1.0, v198
	v_log_f32_e32 v196, v196
	v_cndmask_b32_e64 v238, 0, v195, s[64:65]
	v_max_f32_e32 v195, 0, v197
	v_cndmask_b32_e64 v176, 0, v176, s[28:29]
	v_add_f32_e32 v195, v195, v196
	v_mul_f32_e32 v196, 0x3e0293ee, v78
	v_exp_f32_e64 v197, -|v196|
	v_cndmask_b32_e64 v239, 0, v195, s[66:67]
	v_max_f32_e32 v196, 0, v196
	v_cndmask_b32_e64 v178, 0, v178, s[34:35]
	v_add_f32_e32 v195, 1.0, v197
	v_mul_f32_e32 v197, 0x3e0293ee, v79
	v_log_f32_e32 v195, v195
	v_exp_f32_e64 v198, -|v197|
	v_cndmask_b32_e64 v180, 0, v180, s[38:39]
	v_cmp_lt_i32_e64 s[72:73], 22, v194
	v_add_f32_e32 v195, v196, v195
	v_add_f32_e32 v196, 1.0, v198
	v_log_f32_e32 v196, v196
	v_cndmask_b32_e64 v240, 0, v195, s[68:69]
	v_max_f32_e32 v195, 0, v197
	v_cmp_lt_i32_e64 s[44:45], 4, v194
	v_add_f32_e32 v195, v195, v196
	v_mul_f32_e32 v196, 0x3e0293ee, v80
	v_exp_f32_e64 v197, -|v196|
	v_cndmask_b32_e64 v241, 0, v195, s[70:71]
	v_max_f32_e32 v196, 0, v196
	v_cmp_lt_i32_e64 s[46:47], 5, v194
	v_add_f32_e32 v195, 1.0, v197
	v_mul_f32_e32 v197, 0x3e0293ee, v81
	v_log_f32_e32 v195, v195
	v_exp_f32_e64 v198, -|v197|
	v_cmp_lt_i32_e64 s[50:51], 6, v194
	v_cmp_lt_i32_e64 s[54:55], 7, v194
	v_add_f32_e32 v195, v196, v195
	v_add_f32_e32 v196, 1.0, v198
	v_log_f32_e32 v196, v196
	s_or_b64 s[72:73], s[12:13], s[72:73]
	v_add_f32_e32 v198, v174, v176
	v_add_f32_e32 v199, v175, v177
	v_add_f32_e32 v218, v178, v180
	v_add_f32_e32 v219, v179, v181
	s_or_b64 s[44:45], s[12:13], s[44:45]
	s_or_b64 s[46:47], s[12:13], s[46:47]
	s_or_b64 s[50:51], s[12:13], s[50:51]
	s_or_b64 s[54:55], s[12:13], s[54:55]
	v_cndmask_b32_e64 v242, 0, v195, s[72:73]
	v_max_f32_e32 v195, 0, v197
	v_cmp_lt_i32_e64 s[74:75], 23, v194
	v_add_f32_e32 v198, v198, v218
	v_add_f32_e32 v199, v199, v219
	v_add_f32_e32 v183, v228, v229
	v_add_f32_e32 v185, v230, v231
	v_add_f32_e32 v187, v232, v233
	v_add_f32_e32 v189, v234, v235
	v_cndmask_b32_e64 v182, 0, v182, s[44:45]
	v_cndmask_b32_e64 v184, 0, v184, s[46:47]
	v_cndmask_b32_e64 v186, 0, v186, s[50:51]
	v_cndmask_b32_e64 v188, 0, v188, s[54:55]
	v_add_f32_e32 v195, v195, v196
	s_or_b64 s[12:13], s[12:13], s[74:75]
	v_mov_b32_e32 v175, v199
	v_mov_b32_e32 v177, v199
	v_cndmask_b32_e64 v243, 0, v195, s[12:13]
	v_add_f32_e32 v194, v236, v237
	v_add_f32_e32 v195, v238, v239
	v_permlane32_swap_b32_e32 v175, v177
	v_add_f32_e32 v218, v182, v184
	v_add_f32_e32 v219, v183, v185
	v_add_f32_e32 v220, v186, v188
	v_add_f32_e32 v221, v187, v189
	v_add_f32_e32 v194, v194, v195
	v_add_f32_e32 v195, v240, v241
	v_add_f32_e32 v196, v242, v243
	v_cmp_eq_u32_e64 s[74:75], v175, v199
	v_add_f32_e32 v218, v218, v220
	v_add_f32_e32 v219, v219, v221
	v_add_f32_e32 v196, v195, v196
	v_cndmask_b32_e64 v195, v175, v177, s[74:75]
	v_mov_b32_e32 v175, v219
	v_mov_b32_e32 v177, v219
	s_nop 1
	v_permlane32_swap_b32_e32 v175, v177
	v_cmp_eq_u32_e64 s[74:75], v175, v219
	v_cndmask_b32_e64 v179, 0, v195, s[6:7]
	s_nop 0
	v_cndmask_b32_e64 v197, v175, v177, s[74:75]
	v_cndmask_b32_e64 v175, 0, v197, s[6:7]
	v_add_f32_e32 v175, v173, v175
	v_add_f32_e32 v175, v235, v175
	v_fma_f32 v97, v97, s93, -v175
	v_add_f32_e32 v175, v234, v175
	v_fma_f32 v96, v96, s93, -v175
	v_add_f32_e32 v175, v233, v175
	v_fma_f32 v95, v95, s93, -v175
	v_add_f32_e32 v175, v232, v175
	v_fma_f32 v94, v94, s93, -v175
	v_add_f32_e32 v175, v231, v175
	v_fma_f32 v93, v93, s93, -v175
	v_add_f32_e32 v175, v230, v175
	v_fma_f32 v92, v92, s93, -v175
	v_add_f32_e32 v175, v229, v175
	v_add_f32_e32 v177, v173, v219
	v_fma_f32 v91, v91, s93, -v175
	v_add_f32_e32 v175, v228, v175
	v_fma_f32 v90, v90, s93, -v175
	v_add_f32_e32 v175, v177, v197
	v_add_f32_e32 v175, v179, v175
	v_add_f32_e32 v175, v227, v175
	v_fma_f32 v89, v89, s93, -v175
	v_add_f32_e32 v175, v226, v175
	v_fma_f32 v88, v88, s93, -v175
	v_add_f32_e32 v175, v225, v175
	v_fma_f32 v87, v87, s93, -v175
	v_add_f32_e32 v175, v224, v175
	v_fma_f32 v86, v86, s93, -v175
	v_add_f32_e32 v175, v223, v175
	v_fma_f32 v85, v85, s93, -v175
	v_add_f32_e32 v175, v222, v175
	v_fma_f32 v84, v84, s93, -v175
	v_add_f32_e32 v175, v217, v175
	v_add_f32_e32 v172, v172, v175
	v_fma_f32 v83, v83, s93, -v175
	v_fma_f32 v82, v82, s93, -v172
	v_exp_f32_e32 v83, v83
	v_exp_f32_e32 v82, v82
	v_exp_f32_e32 v85, v85
	v_exp_f32_e32 v84, v84
	v_cndmask_b32_e64 v179, 0, v83, s[10:11]
	v_cndmask_b32_e32 v181, 0, v82, vcc
	v_add_f32_e32 v82, v198, v218
	v_add_f32_e32 v83, v199, v219
	v_cndmask_b32_e64 v175, 0, v85, s[16:17]
	v_cndmask_b32_e64 v177, 0, v84, s[14:15]
	v_add_f32_e32 v84, v194, v196
	v_add_f32_e32 v85, v195, v197
	v_mov_b32_e32 v172, v82
	v_mov_b32_e32 v183, v82
	s_nop 1
	v_permlane32_swap_b32_e32 v172, v183
	v_mov_b32_e32 v185, v84
	v_mov_b32_e32 v187, v84
	s_nop 1
	v_permlane32_swap_b32_e32 v185, v187
	v_cmp_eq_u32_e32 vcc, v172, v82
	v_add_f32_e32 v82, v82, v84
	v_add_f32_e32 v83, v83, v85
	v_exp_f32_e32 v97, v97
	v_cndmask_b32_e32 v183, v172, v183, vcc
	v_cmp_eq_u32_e32 vcc, v185, v84
	v_exp_f32_e32 v96, v96
	v_exp_f32_e32 v95, v95
	v_cndmask_b32_e32 v185, v185, v187, vcc
	v_add_f32_e32 v172, v185, v183
	v_add_f32_e32 v82, v172, v82
	v_add_f32_e32 v83, v173, v83
	v_cndmask_b32_e64 v187, 0, v185, s[6:7]
	v_add_f32_e32 v84, v84, v83
	v_cndmask_b32_e64 v172, 0, v183, s[6:7]
	v_add_f32_e32 v84, v84, v185
	v_add_f32_e32 v85, v187, v83
	v_add_f32_e32 v84, v172, v84
	v_add_f32_e32 v85, v243, v85
	v_add_f32_e32 v84, v188, v84
	v_fma_f32 v81, v81, s93, -v85
	v_add_f32_e32 v85, v242, v85
	v_fma_f32 v73, v73, s93, -v84
	v_add_f32_e32 v84, v186, v84
	v_fma_f32 v80, v80, s93, -v85
	v_add_f32_e32 v85, v241, v85
	v_fma_f32 v72, v72, s93, -v84
	v_add_f32_e32 v84, v184, v84
	v_fma_f32 v79, v79, s93, -v85
	v_add_f32_e32 v85, v240, v85
	v_fma_f32 v71, v71, s93, -v84
	v_add_f32_e32 v84, v182, v84
	v_fma_f32 v78, v78, s93, -v85
	v_add_f32_e32 v85, v239, v85
	v_fma_f32 v70, v70, s93, -v84
	v_add_f32_e32 v84, v180, v84
	v_fma_f32 v77, v77, s93, -v85
	v_add_f32_e32 v85, v238, v85
	v_fma_f32 v69, v69, s93, -v84
	v_add_f32_e32 v84, v178, v84
	v_fma_f32 v76, v76, s93, -v85
	v_add_f32_e32 v85, v237, v85
	v_fma_f32 v68, v68, s93, -v84
	v_add_f32_e32 v84, v176, v84
	v_fma_f32 v75, v75, s93, -v85
	v_add_f32_e32 v85, v236, v85
	v_fma_f32 v67, v67, s93, -v84
	v_add_f32_e32 v84, v174, v84
	v_fma_f32 v74, v74, s93, -v85
	v_fma_f32 v66, v66, s93, -v84
	v_exp_f32_e32 v94, v94
	v_exp_f32_e32 v93, v93
	v_exp_f32_e32 v92, v92
	v_exp_f32_e32 v91, v91
	v_exp_f32_e32 v90, v90
	v_exp_f32_e32 v89, v89
	v_exp_f32_e32 v88, v88
	v_exp_f32_e32 v87, v87
	v_exp_f32_e32 v86, v86
	v_exp_f32_e32 v81, v81
	v_exp_f32_e32 v80, v80
	v_exp_f32_e32 v79, v79
	v_exp_f32_e32 v78, v78
	v_exp_f32_e32 v77, v77
	v_exp_f32_e32 v76, v76
	v_exp_f32_e32 v75, v75
	v_exp_f32_e32 v74, v74
	v_exp_f32_e32 v73, v73
	v_exp_f32_e32 v72, v72
	v_exp_f32_e32 v71, v71
	v_exp_f32_e32 v70, v70
	v_exp_f32_e32 v69, v69
	v_exp_f32_e32 v68, v68
	v_exp_f32_e32 v67, v67
	v_exp_f32_e32 v66, v66
	v_cndmask_b32_e64 v97, 0, v97, s[58:59]
	v_cndmask_b32_e64 v96, 0, v96, s[56:57]
	s_movk_i32 s57, 0x1000
	v_cndmask_b32_e64 v95, 0, v95, s[52:53]
	v_cndmask_b32_e64 v94, 0, v94, s[48:49]
	v_cndmask_b32_e64 v93, 0, v93, s[42:43]
	v_cndmask_b32_e64 v92, 0, v92, s[40:41]
	v_cndmask_b32_e64 v91, 0, v91, s[36:37]
	v_cndmask_b32_e64 v90, 0, v90, s[30:31]
	v_cndmask_b32_e64 v89, 0, v89, s[24:25]
	v_cndmask_b32_e64 v88, 0, v88, s[22:23]
	v_cndmask_b32_e64 v87, 0, v87, s[20:21]
	v_cndmask_b32_e64 v86, 0, v86, s[18:19]
	v_cndmask_b32_e64 v81, 0, v81, s[12:13]
	v_cndmask_b32_e64 v80, 0, v80, s[72:73]
	v_cndmask_b32_e64 v79, 0, v79, s[70:71]
	v_cndmask_b32_e64 v78, 0, v78, s[68:69]
	v_cndmask_b32_e64 v77, 0, v77, s[66:67]
	v_cndmask_b32_e64 v76, 0, v76, s[64:65]
	v_cndmask_b32_e64 v75, 0, v75, s[62:63]
	v_cndmask_b32_e64 v74, 0, v74, s[60:61]
	v_cndmask_b32_e64 v73, 0, v73, s[54:55]
	v_cndmask_b32_e64 v72, 0, v72, s[50:51]
	v_cndmask_b32_e64 v71, 0, v71, s[46:47]
	v_cndmask_b32_e64 v70, 0, v70, s[44:45]
	v_cndmask_b32_e64 v69, 0, v69, s[38:39]
	v_cndmask_b32_e64 v68, 0, v68, s[34:35]
	v_cndmask_b32_e64 v67, 0, v67, s[28:29]
	v_cndmask_b32_e64 v66, 0, v66, s[26:27]
	v_add_f32_e32 v173, v82, v83
	s_mov_b32 s10, 0x43200000
	v_cvt_pk_bf16_f32 v66, v66, v67
	v_cvt_pk_bf16_f32 v67, v68, v69
	v_cvt_pk_bf16_f32 v68, v70, v71
	v_cvt_pk_bf16_f32 v69, v72, v73
	v_cvt_pk_bf16_f32 v70, v74, v75
	v_cvt_pk_bf16_f32 v71, v76, v77
	v_cvt_pk_bf16_f32 v72, v78, v79
	v_cvt_pk_bf16_f32 v73, v80, v81
	v_cvt_pk_bf16_f32 v74, v181, v179
	v_cvt_pk_bf16_f32 v75, v177, v175
	v_cvt_pk_bf16_f32 v76, v86, v87
	v_cvt_pk_bf16_f32 v77, v88, v89
	v_cvt_pk_bf16_f32 v78, v90, v91
	v_cvt_pk_bf16_f32 v79, v92, v93
	v_cvt_pk_bf16_f32 v80, v94, v95
	v_cvt_pk_bf16_f32 v81, v96, v97
	v_cmp_le_f32_e32 vcc, s10, v173
	s_waitcnt lgkmcnt(3)
	v_mfma_f32_32x32x16_bf16 v[50:65], v[158:161], v[66:69], v[50:65]
	s_waitcnt lgkmcnt(2)
	v_mfma_f32_32x32x16_bf16 v[50:65], v[154:157], v[70:73], v[50:65]
	s_waitcnt lgkmcnt(1)
	v_mfma_f32_32x32x16_bf16 v[50:65], v[150:153], v[74:77], v[50:65]
	v_add_u32_e32 v150, v216, v212
	ds_read_b128 v[82:85], v150 offset:22016
	ds_read_b128 v[86:89], v150 offset:22048
	ds_read_b128 v[90:93], v150 offset:22080
	ds_read_b128 v[94:97], v150 offset:22112
	s_waitcnt lgkmcnt(4)
	v_mfma_f32_32x32x16_bf16 v[50:65], v[146:149], v[78:81], v[50:65]
	s_waitcnt lgkmcnt(3)
	v_mfma_f32_32x32x16_bf16 v[34:49], v[82:85], v[66:69], v[34:49]
	s_waitcnt lgkmcnt(2)
	v_mfma_f32_32x32x16_bf16 v[34:49], v[86:89], v[70:73], v[34:49]
	s_waitcnt lgkmcnt(1)
	v_mfma_f32_32x32x16_bf16 v[34:49], v[90:93], v[74:77], v[34:49]
	ds_read_b128 v[82:85], v150 offset:26624
	ds_read_b128 v[86:89], v150 offset:26656
	ds_read_b128 v[90:93], v150 offset:26688
	ds_read_b128 v[146:149], v150 offset:26720
	s_waitcnt lgkmcnt(4)
	v_mfma_f32_32x32x16_bf16 v[34:49], v[94:97], v[78:81], v[34:49]
	s_waitcnt lgkmcnt(3)
	v_mfma_f32_32x32x16_bf16 v[18:33], v[82:85], v[66:69], v[18:33]
	s_waitcnt lgkmcnt(2)
	v_mfma_f32_32x32x16_bf16 v[18:33], v[86:89], v[70:73], v[18:33]
	s_waitcnt lgkmcnt(1)
	v_mfma_f32_32x32x16_bf16 v[18:33], v[90:93], v[74:77], v[18:33]
	ds_read_b128 v[82:85], v150 offset:31232
	ds_read_b128 v[86:89], v150 offset:31264
	ds_read_b128 v[90:93], v150 offset:31296
	ds_read_b128 v[94:97], v150 offset:31328
	s_waitcnt lgkmcnt(4)
	v_mfma_f32_32x32x16_bf16 v[18:33], v[146:149], v[78:81], v[18:33]
	s_waitcnt lgkmcnt(3)
	v_mfma_f32_32x32x16_bf16 v[2:17], v[82:85], v[66:69], v[2:17]
	s_cmp_eq_u64 vcc, exec
	s_cselect_b64 s[10:11], -1, 0
	s_waitcnt lgkmcnt(2)
	v_mfma_f32_32x32x16_bf16 v[2:17], v[86:89], v[70:73], v[2:17]
	s_waitcnt lgkmcnt(1)
	v_mfma_f32_32x32x16_bf16 v[2:17], v[90:93], v[74:77], v[2:17]
	s_waitcnt lgkmcnt(0)
	v_mfma_f32_32x32x16_bf16 v[2:17], v[94:97], v[78:81], v[2:17]
	s_andn2_b64 s[0:1], s[0:1], exec
	s_and_b64 s[10:11], s[10:11], exec
	s_or_b64 s[0:1], s[0:1], s[10:11]
